# RESA (residual+norm) row loop software-pipelined: all modulation/gain vector loads of a row issued together, next row's x/y loads prefetched into spare registers, counted vmcnt
# baseline (speedup 1.0000x reference)
.LBB0_57:
	s_andn2_b64 vcc, exec, s[2:3]
	s_cbranch_vccnz .LBB0_66
	v_lshl_or_b32 v19, v162, 2, v230
	v_cmp_gt_i32_e32 vcc, s24, v19
	s_and_saveexec_b64 s[40:41], vcc
	s_cbranch_execz .LBB0_65
	v_cmp_lt_i32_e32 vcc, v207, v206
	v_lshlrev_b32_e32 v2, 3, v229
	v_mov_b32_e32 v3, v1
	v_cndmask_b32_e32 v0, v205, v207, vcc
	v_lshlrev_b32_e32 v78, 2, v0
	v_xor_b32_e32 v0, 16, v205
	v_cmp_lt_i32_e32 vcc, v0, v206
	v_lshl_add_u64 v[2:3], s[36:37], 0, v[2:3]
	s_mov_b64 s[0:1], 0xbccd800
	v_cndmask_b32_e32 v0, v205, v0, vcc
	v_lshlrev_b32_e32 v79, 2, v0
	v_xor_b32_e32 v0, 8, v205
	v_cmp_lt_i32_e32 vcc, v0, v206
	v_lshl_add_u64 v[20:21], v[2:3], 0, s[0:1]
	s_mov_b64 s[0:1], 0xddcd800
	v_cndmask_b32_e32 v0, v205, v0, vcc
	v_lshlrev_b32_e32 v80, 2, v0
	v_xor_b32_e32 v0, 4, v205
	v_cmp_lt_i32_e32 vcc, v0, v206
	v_lshl_add_u64 v[22:23], v[2:3], 0, s[0:1]
	v_readlane_b32 s0, v255, 30
	v_cndmask_b32_e32 v0, v205, v0, vcc
	v_readlane_b32 s1, v255, 31
	s_lshl_b32 s96, s0, 10
	v_lshlrev_b32_e32 v81, 2, v0
	v_xor_b32_e32 v0, 2, v205
	s_lshl_b64 s[0:1], s[96:97], 2
	v_cmp_lt_i32_e32 vcc, v0, v206
	s_add_u32 s2, s94, s0
	v_readlane_b32 s4, v253, 1
	v_cndmask_b32_e32 v0, v205, v0, vcc
	s_addc_u32 s3, s95, s1
	s_waitcnt vmcnt(1)
	v_lshlrev_b32_e32 v82, 2, v0
	v_xor_b32_e32 v0, 1, v205
	v_readlane_b32 s12, v253, 9
	v_cmp_lt_i32_e32 vcc, v0, v206
	v_readlane_b32 s13, v253, 10
	s_add_u32 s0, s12, s0
	v_lshlrev_b32_e32 v18, 2, v229
	v_cndmask_b32_e32 v0, v205, v0, vcc
	v_lshlrev_b32_e32 v4, 4, v229
	v_mov_b32_e32 v5, v1
	s_addc_u32 s1, s13, s1
	v_lshlrev_b32_e32 v83, 2, v0
	v_or_b32_e32 v0, 0x100, v18
	v_or_b32_e32 v6, 0x200, v18
	v_or_b32_e32 v8, 0x300, v18
	v_lshl_add_u64 v[26:27], s[0:1], 0, v[4:5]
	s_mov_b64 s[0:1], 0x308d800
	v_lshl_add_u64 v[24:25], s[2:3], 0, v[4:5]
	v_lshl_add_u64 v[28:29], v[2:3], 0, s[0:1]
	v_xad_u32 v30, v19, -1, s24
	s_mov_b64 s[44:45], 0
	v_lshlrev_b32_e32 v32, 2, v0
	v_lshlrev_b32_e32 v34, 2, v6
	v_lshlrev_b32_e32 v36, 2, v8
	v_readlane_b32 s5, v253, 2
	v_readlane_b32 s6, v253, 3
	v_readlane_b32 s7, v253, 4
	v_readlane_b32 s8, v253, 5
	v_readlane_b32 s9, v253, 6
	v_readlane_b32 s10, v253, 7
	v_readlane_b32 s11, v253, 8
	v_readlane_b32 s14, v253, 11
	v_readlane_b32 s15, v253, 12
	v_readlane_b32 s16, v253, 13
	v_readlane_b32 s17, v253, 14
	v_readlane_b32 s18, v253, 15
	v_readlane_b32 s19, v253, 16
	s_mov_b32 s96, 0
	s_branch .LBB0_61
.LBB0_60:
	s_or_b64 exec, exec, s[2:3]
	v_mov_b32_e32 v62, v56
	v_mov_b32_e32 v63, v76
	v_min_i32_e32 v0, 0x4000, v30
	v_readlane_b32 s0, v255, 30
	v_pk_mul_f32 v[62:63], v[62:63], v[62:63]
	v_mov_b32_e32 v64, v57
	v_mov_b32_e32 v65, v77
	v_ashrrev_i32_e32 v0, 13, v0
	v_readlane_b32 s1, v255, 31
	s_mul_i32 s0, s0, 3
	v_pk_fma_f32 v[62:63], v[64:65], v[64:65], v[62:63]
	v_mov_b32_e32 v64, v54
	v_mov_b32_e32 v65, v74
	v_add_u32_e32 v0, s0, v0
	v_readlane_b32 s0, v255, 6
	v_pk_fma_f32 v[62:63], v[64:65], v[64:65], v[62:63]
	v_mov_b32_e32 v64, v55
	v_mov_b32_e32 v65, v75
	v_readlane_b32 s1, v255, 7
	v_pk_fma_f32 v[62:63], v[64:65], v[64:65], v[62:63]
	v_mov_b32_e32 v64, v44
	v_mov_b32_e32 v65, v52
	v_mov_b64_e32 v[48:49], s[0:1]
	s_movk_i32 s0, 0x6000
	v_pk_mul_f32 v[64:65], v[64:65], v[64:65]
	v_mov_b32_e32 v66, v45
	v_mov_b32_e32 v67, v53
	v_mad_i64_i32 v[48:49], s[0:1], v0, s0, v[48:49]
	v_pk_fma_f32 v[64:65], v[66:67], v[66:67], v[64:65]
	v_mov_b32_e32 v66, v46
	v_mov_b32_e32 v67, v50
	s_mov_b64 s[0:1], 0x2000
	v_pk_fma_f32 v[64:65], v[66:67], v[66:67], v[64:65]
	v_mov_b32_e32 v66, v47
	v_mov_b32_e32 v67, v51
	v_lshl_add_u64 v[60:61], v[48:49], 0, s[0:1]
	v_pk_fma_f32 v[64:65], v[66:67], v[66:67], v[64:65]
	v_add_f32_e32 v0, v62, v63
	v_mov_b32_e32 v39, v1
	v_add_f32_e32 v0, v65, v0
	v_lshl_add_u64 v[62:63], v[60:61], 0, v[38:39]
	v_mov_b32_e32 v33, v1
	v_mov_b32_e32 v35, v1
	v_mov_b32_e32 v37, v1
	v_add_f32_e32 v0, v64, v0
	v_lshl_add_u64 v[66:67], v[60:61], 0, v[32:33]
	v_lshl_add_u64 v[68:69], v[60:61], 0, v[34:35]
	v_lshl_add_u64 v[70:71], v[60:61], 0, v[36:37]
	v_lshl_add_u64 v[42:43], v[42:43], 0, v[58:59]
	global_load_dwordx4 v[58:61], v[24:25], off
	s_nop 0
	global_load_dwordx4 v[62:65], v[62:63], off
	global_load_dwordx4 v[90:93], v[24:25], off offset:1024
	global_load_dwordx4 v[94:97], v[66:67], off
	global_load_dwordx4 v[98:101], v[24:25], off offset:2048
	global_load_dwordx4 v[102:105], v[68:69], off
	global_load_dwordx4 v[106:109], v[24:25], off offset:3072
	global_load_dwordx4 v[110:113], v[70:71], off
	s_mov_b64 s[98:99], 0x3000
	v_lshl_add_u64 v[174:175], v[48:49], 0, s[98:99]
	v_lshl_add_u64 v[176:177], v[48:49], 0, s[28:29]
	v_lshl_add_u64 v[174:175], v[174:175], 0, v[38:39]
	v_lshl_add_u64 v[176:177], v[176:177], 0, v[38:39]
	global_load_dwordx4 v[178:181], v[26:27], off
	global_load_dwordx4 v[182:185], v[176:177], off
	global_load_dwordx4 v[186:189], v[174:175], off
	global_load_dwordx4 v[114:117], v[26:27], off offset:1024
	global_load_dwordx4 v[118:121], v[176:177], off offset:1024
	global_load_dwordx4 v[122:125], v[174:175], off offset:1024
	global_load_dwordx4 v[126:129], v[26:27], off offset:2048
	global_load_dwordx4 v[130:133], v[176:177], off offset:2048
	global_load_dwordx4 v[134:137], v[174:175], off offset:2048
	global_load_dwordx4 v[138:141], v[26:27], off offset:3072
	global_load_dwordx4 v[142:145], v[176:177], off offset:3072
	global_load_dwordx4 v[146:149], v[174:175], off offset:3072
	v_readlane_b32 s32, v255, 8
	s_nop 3
	v_add_u32_e32 v190, s32, v19
	v_cmp_gt_i32_e32 vcc, s24, v190
	v_subrev_u32_e32 v190, s32, v30
	s_mov_b32 s96, 0
	s_nop 2
	v_cndmask_b32_e32 v190, v30, v190, vcc
	s_cbranch_vccz .Lra_nonext
	s_mov_b32 s96, 1
.Lra_nonext:
	v_mov_b32_e32 v191, v1
	s_and_b64 s[0:1], s[38:39], exec
	s_cselect_b32 s0, s50, s80
	s_cselect_b32 s1, s51, s81
	v_lshlrev_b64 v[192:193], 12, v[190:191]
	v_lshlrev_b64 v[194:195], 11, v[190:191]
	v_lshl_add_u64 v[192:193], s[0:1], 0, v[192:193]
	v_lshl_add_u64 v[194:195], v[20:21], 0, v[194:195]
	v_lshl_add_u64 v[192:193], v[192:193], 0, v[38:39]
	global_load_dwordx4 v[150:153], v[192:193], off nt
	global_load_dwordx4 v[154:157], v[192:193], off offset:1024 nt
	global_load_dwordx4 v[158:161], v[192:193], off offset:2048 nt
	global_load_dwordx4 v[162:165], v[192:193], off offset:3072 nt
	global_load_dwordx2 v[166:167], v[194:195], off nt
	global_load_dwordx2 v[168:169], v[194:195], off offset:512 nt
	global_load_dwordx2 v[170:171], v[194:195], off offset:1024 nt
	global_load_dwordx2 v[172:173], v[194:195], off offset:1536 nt
	ds_bpermute_b32 v31, v78, v0
	s_mov_b32 s2, 0x800000
	v_lshl_add_u64 v[42:43], v[42:43], 0, v[38:39]
	s_mov_b64 s[0:1], 0x3000
	s_mov_b32 s66, 0x800000
	s_waitcnt lgkmcnt(0)
	v_add_f32_e32 v0, v0, v31
	ds_bpermute_b32 v31, v79, v0
	s_waitcnt lgkmcnt(0)
	v_add_f32_e32 v0, v0, v31
	ds_bpermute_b32 v31, v80, v0
	s_waitcnt lgkmcnt(0)
	v_add_f32_e32 v0, v0, v31
	ds_bpermute_b32 v31, v81, v0
	s_waitcnt lgkmcnt(0)
	v_add_f32_e32 v0, v0, v31
	ds_bpermute_b32 v31, v82, v0
	s_waitcnt lgkmcnt(0)
	v_add_f32_e32 v0, v0, v31
	ds_bpermute_b32 v31, v83, v0
	s_waitcnt lgkmcnt(0)
	v_add_f32_e32 v0, v0, v31
	v_fmamk_f32 v0, v0, 0x3a800000, v201
	v_cmp_gt_f32_e32 vcc, s2, v0
	v_mul_f32_e32 v31, 0x4b800000, v0
	s_nop 0
	v_cndmask_b32_e32 v0, v0, v31, vcc
	v_rsq_f32_e32 v0, v0
	s_nop 0
	v_mul_f32_e32 v31, 0x45800000, v0
	v_cndmask_b32_e32 v0, v0, v31, vcc
	v_pk_mul_f32 v[72:73], v[76:77], v[0:1] op_sel_hi:[1,0]
	v_pk_mul_f32 v[56:57], v[56:57], v[0:1] op_sel_hi:[1,0]
	v_pk_mul_f32 v[54:55], v[54:55], v[0:1] op_sel_hi:[1,0]
	v_pk_mul_f32 v[52:53], v[52:53], v[0:1] op_sel_hi:[1,0]
	v_pk_mul_f32 v[50:51], v[50:51], v[0:1] op_sel_hi:[1,0]
	v_pk_mul_f32 v[44:45], v[44:45], v[0:1] op_sel_hi:[1,0]
	s_waitcnt vmcnt(27)
	v_pk_mul_f32 v[58:59], v[58:59], v[72:73]
	s_waitcnt vmcnt(26)
	v_pk_fma_f32 v[14:15], v[62:63], v[58:59], v[14:15]
	v_pk_mul_f32 v[58:59], v[74:75], v[0:1] op_sel_hi:[1,0]
	s_nop 0
	v_pk_mul_f32 v[58:59], v[60:61], v[58:59]
	s_nop 0
	v_pk_fma_f32 v[16:17], v[64:65], v[58:59], v[16:17]
	s_waitcnt vmcnt(25)
	v_pk_mul_f32 v[56:57], v[90:91], v[56:57]
	v_pk_mul_f32 v[54:55], v[92:93], v[54:55]
	s_waitcnt vmcnt(24)
	v_pk_fma_f32 v[10:11], v[94:95], v[56:57], v[10:11]
	v_pk_fma_f32 v[12:13], v[54:55], v[96:97], v[12:13]
	s_waitcnt vmcnt(23)
	v_pk_mul_f32 v[52:53], v[52:53], v[98:99]
	v_pk_mul_f32 v[50:51], v[50:51], v[100:101]
	s_waitcnt vmcnt(22)
	v_pk_fma_f32 v[6:7], v[52:53], v[102:103], v[6:7]
	v_pk_fma_f32 v[8:9], v[50:51], v[104:105], v[8:9]
	s_waitcnt vmcnt(21)
	v_pk_mul_f32 v[44:45], v[44:45], v[106:107]
	s_waitcnt vmcnt(20)
	v_pk_fma_f32 v[2:3], v[44:45], v[110:111], v[2:3]
	v_pk_mul_f32 v[44:45], v[46:47], v[0:1] op_sel_hi:[1,0]
	v_mov_b32_e32 v46, v14
	v_pk_mul_f32 v[44:45], v[44:45], v[108:109]
	v_mov_b32_e32 v47, v10
	v_pk_fma_f32 v[4:5], v[44:45], v[112:113], v[4:5]
	global_store_dwordx4 v[42:43], v[14:17], off
	global_store_dwordx4 v[42:43], v[10:13], off offset:1024
	global_store_dwordx4 v[42:43], v[6:9], off offset:2048
	global_store_dwordx4 v[42:43], v[2:5], off offset:3072
	v_lshl_add_u64 v[42:43], v[48:49], 0, s[0:1]
	v_lshl_add_u64 v[44:45], v[48:49], 0, s[28:29]
	v_mov_b32_e32 v48, v15
	v_mov_b32_e32 v49, v11
	v_pk_mul_f32 v[48:49], v[48:49], v[48:49]
	v_mov_b32_e32 v50, v7
	v_pk_fma_f32 v[46:47], v[46:47], v[46:47], v[48:49]
	v_mov_b32_e32 v48, v16
	v_mov_b32_e32 v49, v12
	v_pk_fma_f32 v[46:47], v[48:49], v[48:49], v[46:47]
	v_mov_b32_e32 v48, v17
	v_mov_b32_e32 v49, v13
	v_mov_b32_e32 v51, v3
	v_pk_fma_f32 v[46:47], v[48:49], v[48:49], v[46:47]
	v_mov_b32_e32 v48, v6
	v_mov_b32_e32 v49, v2
	v_pk_mul_f32 v[50:51], v[50:51], v[50:51]
	v_add_f32_e32 v0, v46, v47
	v_pk_fma_f32 v[48:49], v[48:49], v[48:49], v[50:51]
	v_mov_b32_e32 v50, v8
	v_mov_b32_e32 v51, v4
	v_pk_fma_f32 v[48:49], v[50:51], v[50:51], v[48:49]
	v_mov_b32_e32 v50, v9
	v_mov_b32_e32 v51, v5
	v_pk_fma_f32 v[48:49], v[50:51], v[50:51], v[48:49]
	v_lshl_add_u64 v[50:51], v[44:45], 0, v[38:39]
	v_add_f32_e32 v0, v0, v48
	v_lshl_add_u64 v[54:55], v[42:43], 0, v[38:39]
	v_add_f32_e32 v0, v0, v49
	ds_bpermute_b32 v31, v78, v0
	v_lshl_add_u64 v[38:39], v[28:29], 0, v[40:41]
	v_readlane_b32 s0, v255, 8
	v_readlane_b32 s1, v255, 9
	s_waitcnt lgkmcnt(0)
	v_add_f32_e32 v0, v0, v31
	ds_bpermute_b32 v31, v79, v0
	v_add_u32_e32 v19, s0, v19
	v_subrev_u32_e32 v30, s0, v30
	s_waitcnt lgkmcnt(0)
	v_add_f32_e32 v0, v0, v31
	ds_bpermute_b32 v31, v80, v0
	s_waitcnt lgkmcnt(0)
	v_add_f32_e32 v0, v0, v31
	ds_bpermute_b32 v31, v81, v0
	s_waitcnt lgkmcnt(0)
	v_add_f32_e32 v0, v0, v31
	ds_bpermute_b32 v31, v82, v0
	s_waitcnt lgkmcnt(0)
	v_add_f32_e32 v0, v0, v31
	ds_bpermute_b32 v31, v83, v0
	s_waitcnt lgkmcnt(0)
	v_add_f32_e32 v0, v0, v31
	v_fmamk_f32 v0, v0, 0x3a800000, v201
	v_cmp_gt_f32_e32 vcc, s2, v0
	v_mul_f32_e32 v31, 0x4b800000, v0
	s_waitcnt vmcnt(21)
	v_pk_add_f32 v[40:41], v[182:183], 1.0 op_sel_hi:[1,0]
	v_cndmask_b32_e32 v0, v0, v31, vcc
	v_rsq_f32_e32 v0, v0
	v_lshl_add_u64 v[50:51], v[42:43], 0, v[32:33]
	v_mul_f32_e32 v31, 0x45800000, v0
	v_cndmask_b32_e32 v0, v0, v31, vcc
	v_pk_mul_f32 v[14:15], v[14:15], v[0:1] op_sel_hi:[1,0]
	v_pk_mul_f32 v[16:17], v[16:17], v[0:1] op_sel_hi:[1,0]
	v_pk_mul_f32 v[14:15], v[178:179], v[14:15]
	v_pk_mul_f32 v[16:17], v[180:181], v[16:17]
	v_pk_fma_f32 v[14:15], v[40:41], v[14:15], v[186:187]
	v_pk_add_f32 v[40:41], v[184:185], 1.0 op_sel_hi:[1,0]
	v_cvt_pk_bf16_f32 v14, v14, v15
	v_pk_fma_f32 v[16:17], v[40:41], v[16:17], v[188:189]
	v_lshl_add_u64 v[40:41], v[44:45], 0, v[32:33]
	v_cvt_pk_bf16_f32 v15, v16, v17
	global_store_dwordx2 v[38:39], v[14:15], off
	v_pk_mul_f32 v[10:11], v[10:11], v[0:1] op_sel_hi:[1,0]
	v_pk_mul_f32 v[12:13], v[12:13], v[0:1] op_sel_hi:[1,0]
	v_lshl_add_u64 v[40:41], v[42:43], 0, v[34:35]
	v_pk_mul_f32 v[6:7], v[6:7], v[0:1] op_sel_hi:[1,0]
	v_pk_mul_f32 v[8:9], v[8:9], v[0:1] op_sel_hi:[1,0]
	v_pk_mul_f32 v[2:3], v[2:3], v[0:1] op_sel_hi:[1,0]
	v_pk_mul_f32 v[4:5], v[4:5], v[0:1] op_sel_hi:[1,0]
	v_cmp_le_i32_e32 vcc, s24, v19
	s_or_b64 s[44:45], vcc, s[44:45]
	s_waitcnt vmcnt(19)
	v_pk_mul_f32 v[10:11], v[10:11], v[114:115]
	v_pk_add_f32 v[14:15], v[118:119], 1.0 op_sel_hi:[1,0]
	v_pk_mul_f32 v[12:13], v[12:13], v[116:117]
	v_pk_fma_f32 v[10:11], v[10:11], v[14:15], v[122:123]
	v_pk_add_f32 v[14:15], v[120:121], 1.0 op_sel_hi:[1,0]
	v_cvt_pk_bf16_f32 v10, v10, v11
	v_pk_fma_f32 v[12:13], v[12:13], v[14:15], v[124:125]
	v_lshl_add_u64 v[14:15], v[44:45], 0, v[34:35]
	v_cvt_pk_bf16_f32 v11, v12, v13
	global_store_dwordx2 v[38:39], v[10:11], off offset:512
	s_waitcnt vmcnt(17)
	v_pk_mul_f32 v[6:7], v[6:7], v[126:127]
	v_pk_add_f32 v[10:11], v[130:131], 1.0 op_sel_hi:[1,0]
	v_pk_mul_f32 v[8:9], v[8:9], v[128:129]
	v_pk_fma_f32 v[6:7], v[6:7], v[10:11], v[134:135]
	v_pk_add_f32 v[10:11], v[132:133], 1.0 op_sel_hi:[1,0]
	v_cvt_pk_bf16_f32 v6, v6, v7
	v_pk_fma_f32 v[8:9], v[8:9], v[10:11], v[136:137]
	v_lshl_add_u64 v[10:11], v[44:45], 0, v[36:37]
	v_cvt_pk_bf16_f32 v7, v8, v9
	global_store_dwordx2 v[38:39], v[6:7], off offset:1024
	v_lshl_add_u64 v[14:15], v[42:43], 0, v[36:37]
	s_waitcnt vmcnt(15)
	v_pk_mul_f32 v[2:3], v[2:3], v[138:139]
	v_pk_add_f32 v[6:7], v[142:143], 1.0 op_sel_hi:[1,0]
	v_pk_mul_f32 v[4:5], v[4:5], v[140:141]
	v_pk_fma_f32 v[2:3], v[2:3], v[6:7], v[146:147]
	v_pk_add_f32 v[6:7], v[144:145], 1.0 op_sel_hi:[1,0]
	v_cvt_pk_bf16_f32 v2, v2, v3
	v_pk_fma_f32 v[4:5], v[4:5], v[6:7], v[148:149]
	s_nop 0
	v_cvt_pk_bf16_f32 v3, v4, v5
	global_store_dwordx2 v[38:39], v[2:3], off offset:1536
	s_andn2_b64 exec, exec, s[44:45]
	s_cbranch_execz .LBB0_65
.LBB0_61:
	s_movk_i32 s0, 0x4000
	v_add_u32_e32 v0, 0xffffc000, v30
	v_ashrrev_i32_e32 v31, 31, v30
	v_cmp_gt_i32_e32 vcc, s0, v30
	v_mov_b32_e32 v4, s81
	v_lshlrev_b32_e32 v38, 2, v18
	v_cndmask_b32_e32 v3, 0, v31, vcc
	v_cndmask_b32_e32 v2, v0, v30, vcc
	v_lshlrev_b64 v[58:59], 12, v[2:3]
	v_mov_b32_e32 v2, s63
	v_mov_b32_e32 v3, s51
	v_cndmask_b32_e32 v43, v2, v3, vcc
	v_mov_b32_e32 v2, s62
	v_mov_b32_e32 v3, s50
	v_cndmask_b32_e32 v42, v2, v3, vcc
	v_mov_b32_e32 v2, s84
	v_mov_b32_e32 v3, s80
	v_cndmask_b32_e32 v2, v2, v3, vcc
	v_mov_b32_e32 v3, s85
	v_cndmask_b32_e32 v3, v3, v4, vcc
	v_cndmask_b32_e64 v3, v3, v43, s[38:39]
	v_cndmask_b32_e64 v2, v2, v42, s[38:39]
	v_lshl_add_u64 v[2:3], v[2:3], 0, v[58:59]
	v_mov_b32_e32 v39, v1
	v_lshl_add_u64 v[2:3], v[2:3], 0, v[38:39]
	s_cmp_lg_u32 s96, 0
	s_cbranch_scc1 .Lra_pfx
	global_load_dwordx4 v[14:17], v[2:3], off nt
	global_load_dwordx4 v[10:13], v[2:3], off offset:1024 nt
	global_load_dwordx4 v[6:9], v[2:3], off offset:2048 nt
	s_nop 0
	global_load_dwordx4 v[2:5], v[2:3], off offset:3072 nt
	s_branch .Lra_xj
.Lra_pfx:
	s_waitcnt vmcnt(8)
	v_mov_b32_e32 v14, v150
	v_mov_b32_e32 v15, v151
	v_mov_b32_e32 v16, v152
	v_mov_b32_e32 v17, v153
	v_mov_b32_e32 v10, v154
	v_mov_b32_e32 v11, v155
	v_mov_b32_e32 v12, v156
	v_mov_b32_e32 v13, v157
	v_mov_b32_e32 v6, v158
	v_mov_b32_e32 v7, v159
	v_mov_b32_e32 v8, v160
	v_mov_b32_e32 v9, v161
	v_mov_b32_e32 v2, v162
	v_mov_b32_e32 v3, v163
	v_mov_b32_e32 v4, v164
	v_mov_b32_e32 v5, v165
.Lra_xj:
	v_lshlrev_b64 v[40:41], 11, v[30:31]
	s_and_saveexec_b64 s[0:1], vcc
	s_xor_b64 s[2:3], exec, s[0:1]
	s_cbranch_execz .LBB0_63
	v_lshlrev_b64 v[40:41], 11, v[30:31]
	s_cmp_lg_u32 s96, 0
	s_cbranch_scc1 .Lra_pfy
	v_lshl_add_u64 v[44:45], v[20:21], 0, v[40:41]
	global_load_dwordx2 v[46:47], v[44:45], off nt
	global_load_dwordx2 v[48:49], v[44:45], off offset:512 nt
	global_load_dwordx2 v[50:51], v[44:45], off offset:1024 nt
	global_load_dwordx2 v[60:61], v[44:45], off offset:1536 nt
	s_waitcnt vmcnt(3)
	v_lshlrev_b32_e32 v76, 16, v46
	v_and_b32_e32 v77, 0xffff0000, v46
	v_lshlrev_b32_e32 v74, 16, v47
	v_and_b32_e32 v75, 0xffff0000, v47
	s_waitcnt vmcnt(2)
	v_lshlrev_b32_e32 v56, 16, v48
	v_and_b32_e32 v57, 0xffff0000, v48
	v_lshlrev_b32_e32 v54, 16, v49
	v_and_b32_e32 v55, 0xffff0000, v49
	s_waitcnt vmcnt(1)
	v_lshlrev_b32_e32 v52, 16, v50
	v_and_b32_e32 v53, 0xffff0000, v50
	v_lshlrev_b32_e32 v50, 16, v51
	v_and_b32_e32 v51, 0xffff0000, v51
	s_waitcnt vmcnt(0)
	v_lshlrev_b32_e32 v44, 16, v60
	v_and_b32_e32 v45, 0xffff0000, v60
	v_lshlrev_b32_e32 v46, 16, v61
	v_and_b32_e32 v47, 0xffff0000, v61
	s_branch .LBB0_63
.Lra_pfy:
	v_lshlrev_b32_e32 v76, 16, v166
	v_and_b32_e32 v77, 0xffff0000, v166
	v_lshlrev_b32_e32 v74, 16, v167
	v_and_b32_e32 v75, 0xffff0000, v167
	v_lshlrev_b32_e32 v56, 16, v168
	v_and_b32_e32 v57, 0xffff0000, v168
	v_lshlrev_b32_e32 v54, 16, v169
	v_and_b32_e32 v55, 0xffff0000, v169
	v_lshlrev_b32_e32 v52, 16, v170
	v_and_b32_e32 v53, 0xffff0000, v170
	v_lshlrev_b32_e32 v50, 16, v171
	v_and_b32_e32 v51, 0xffff0000, v171
	v_lshlrev_b32_e32 v44, 16, v172
	v_and_b32_e32 v45, 0xffff0000, v172
	v_lshlrev_b32_e32 v46, 16, v173
	v_and_b32_e32 v47, 0xffff0000, v173
	s_branch .LBB0_63

.LBB0_65:
	s_or_b64 exec, exec, s[40:41]
	s_waitcnt vmcnt(0)
